# EpiBranch epilogue: pipelined G/M32 loads (saddr form, 5-deep) instead of serialized load-wait-store ladder
# baseline (speedup 1.0000x reference)
; __device__ __forceinline__ unsigned cvt_pk_bf16(float lo, float hi) { f32x2 v = {lo, hi}; bf16x2_t b = __builtin_convertvector(v, bf16x2_t); return __builtin_bit_cast(unsigned, b); }
; __device__ __forceinline__ float bf_lo(unsigned w) { return __uint_as_float(w << 16); }
; __device__ __forceinline__ float bf_hi(unsigned w) { return __uint_as_float(w & 0xffff0000u); }
;     __device__ __forceinline__ void operator()(ACC_T, const Unit& u, int wr, int wc, int fr, int fq) const {
;         const int row0 = u.pm * BM + wr * 64 + fr, col0 = u.pn * BM + wc * 32 + 8 * fq;
; #pragma unroll
;         for (int ai = 0; ai < 2; ++ai)
; #pragma unroll
;             for (int m = 0; m < 4; ++m) { const size_t row = (size_t)(row0 + ai * HALF + m * 16);
; #pragma unroll
;                 for (int bj = 0; bj < 2; ++bj) {
;                     const u32x4 gw = *(const u32x4*)(Gt + row * GW + u.z * DM + col0 + bj * HALF);
;                     f32x4 v0 = acc[ai][bj][m][0], v1 = acc[ai][bj][m][1];
;                     v0[0] *= bf_lo(gw.x); v0[1] *= bf_hi(gw.x); v0[2] *= bf_lo(gw.y); v0[3] *= bf_hi(gw.y);
;                     v1[0] *= bf_lo(gw.z); v1[1] *= bf_hi(gw.z); v1[2] *= bf_lo(gw.w); v1[3] *= bf_hi(gw.w);
;                     float* mp = M32 + (size_t)u.pm * (SLOTB / 4) + (row - (size_t)u.pm * BM) * DM + col0 + bj * HALF;
;                     if (u.z > 0) { v0 += *(const f32x4*)mp; v1 += *(const f32x4*)(mp + 4); }
;                     if (u.z < 2) { *(f32x4*)mp = v0; *(f32x4*)(mp + 4) = v1; }
;                     else { u32x4 w; w.x = cvt_pk_bf16(v0[0], v0[1]); w.y = cvt_pk_bf16(v0[2], v0[3]); w.z = cvt_pk_bf16(v1[0], v1[1]); w.w = cvt_pk_bf16(v1[2], v1[3]);
;                         *(u32x4*)(MG + row * DM + col0 + bj * HALF) = w; } } }
.LBB0_667:
	v_readlane_b32 s24, v251, 58
	v_readlane_b32 s25, v251, 59
	v_readlane_b32 s46, v251, 56
	v_readlane_b32 s47, v251, 57
	v_readlane_b32 s22, v254, 52
	v_readlane_b32 s23, v254, 53
	v_lshl_or_b32 v143, s3, 8, v152
	v_mul_u32_u24_e32 v140, 0x1800, v150
	v_lshlrev_b32_e32 v141, 12, v150
	v_lshlrev_b32_e32 v142, 11, v150
	v_lshl_add_u32 v140, v143, 1, v140
	v_lshl_add_u32 v141, v143, 2, v141
	v_lshl_add_u32 v142, v143, 1, v142
	s_mul_i32 s44, s14, 0x180000
	s_lshl_b32 s45, s2, 11
	s_add_u32 s44, s44, s45
	s_add_u32 s24, s24, s44
	s_addc_u32 s25, s25, 0
	s_mul_i32 s44, s14, 0x1c0000
	s_add_u32 s46, s46, s44
	s_addc_u32 s47, s47, 0
	s_mov_b32 s48, s46
	s_mov_b32 s49, s47
	s_lshl_b32 s44, s14, 19
	s_add_u32 s22, s22, s44
	s_addc_u32 s23, s23, 0
	s_cmp_eq_u32 s2, 0
	s_cbranch_scc1 .Lbr_z0
	s_cmp_eq_u32 s2, 1
	s_cbranch_scc1 .Lbr_z1
	global_load_dwordx4 v[144:147], v140, s[24:25]
	global_load_dwordx4 v[154:157], v141, s[46:47]
	global_load_dwordx4 v[158:161], v141, s[46:47] offset:16
	global_load_dwordx4 v[162:165], v140, s[24:25] offset:256
	global_load_dwordx4 v[166:169], v141, s[46:47] offset:512
	global_load_dwordx4 v[170:173], v141, s[46:47] offset:528
	s_add_u32 s24, s24, 0x18000
	s_addc_u32 s25, s25, 0
	s_add_u32 s46, s46, 0x10000
	s_addc_u32 s47, s47, 0
	global_load_dwordx4 v[174:177], v140, s[24:25]
	global_load_dwordx4 v[178:181], v141, s[46:47]
	global_load_dwordx4 v[182:185], v141, s[46:47] offset:16
	global_load_dwordx4 v[186:189], v140, s[24:25] offset:256
	global_load_dwordx4 v[190:193], v141, s[46:47] offset:512
	global_load_dwordx4 v[194:197], v141, s[46:47] offset:528
	s_add_u32 s24, s24, 0x18000
	s_addc_u32 s25, s25, 0
	s_add_u32 s46, s46, 0x10000
	s_addc_u32 s47, s47, 0
	global_load_dwordx4 v[198:201], v140, s[24:25]
	global_load_dwordx4 v[202:205], v141, s[46:47]
	global_load_dwordx4 v[206:209], v141, s[46:47] offset:16
	s_waitcnt vmcnt(12)
	v_lshlrev_b32_e32 v148, 16, v144
	v_and_b32_e32 v149, 0xffff0000, v144
	v_lshlrev_b32_e32 v210, 16, v145
	v_and_b32_e32 v211, 0xffff0000, v145
	v_lshlrev_b32_e32 v212, 16, v146
	v_and_b32_e32 v213, 0xffff0000, v146
	v_lshlrev_b32_e32 v214, 16, v147
	v_and_b32_e32 v215, 0xffff0000, v147
	v_pk_mul_f32 v[126:127], v[126:127], v[148:149]
	v_pk_mul_f32 v[128:129], v[128:129], v[210:211]
	v_pk_mul_f32 v[122:123], v[122:123], v[212:213]
	v_pk_mul_f32 v[124:125], v[124:125], v[214:215]
	v_pk_add_f32 v[126:127], v[126:127], v[154:155]
	v_pk_add_f32 v[128:129], v[128:129], v[156:157]
	v_pk_add_f32 v[122:123], v[122:123], v[158:159]
	v_pk_add_f32 v[124:125], v[124:125], v[160:161]
	v_cvt_pk_bf16_f32 v144, v126, v127
	v_cvt_pk_bf16_f32 v145, v128, v129
	v_cvt_pk_bf16_f32 v146, v122, v123
	v_cvt_pk_bf16_f32 v147, v124, v125
	global_store_dwordx4 v142, v[144:147], s[22:23]
	global_load_dwordx4 v[154:157], v140, s[24:25] offset:256
	global_load_dwordx4 v[158:161], v141, s[46:47] offset:512
	global_load_dwordx4 v[126:129], v141, s[46:47] offset:528
	s_add_u32 s24, s24, 0x18000
	s_addc_u32 s25, s25, 0
	s_add_u32 s46, s46, 0x10000
	s_addc_u32 s47, s47, 0
	s_waitcnt vmcnt(13)
	v_lshlrev_b32_e32 v148, 16, v162
	v_and_b32_e32 v149, 0xffff0000, v162
	v_lshlrev_b32_e32 v210, 16, v163
	v_and_b32_e32 v211, 0xffff0000, v163
	v_lshlrev_b32_e32 v212, 16, v164
	v_and_b32_e32 v213, 0xffff0000, v164
	v_lshlrev_b32_e32 v214, 16, v165
	v_and_b32_e32 v215, 0xffff0000, v165
	v_pk_mul_f32 v[118:119], v[118:119], v[148:149]
	v_pk_mul_f32 v[120:121], v[120:121], v[210:211]
	v_pk_mul_f32 v[114:115], v[114:115], v[212:213]
	v_pk_mul_f32 v[116:117], v[116:117], v[214:215]
	v_pk_add_f32 v[118:119], v[118:119], v[166:167]
	v_pk_add_f32 v[120:121], v[120:121], v[168:169]
	v_pk_add_f32 v[114:115], v[114:115], v[170:171]
	v_pk_add_f32 v[116:117], v[116:117], v[172:173]
	v_cvt_pk_bf16_f32 v162, v118, v119
	v_cvt_pk_bf16_f32 v163, v120, v121
	v_cvt_pk_bf16_f32 v164, v114, v115
	v_cvt_pk_bf16_f32 v165, v116, v117
	global_store_dwordx4 v142, v[162:165], s[22:23] offset:256
	s_add_u32 s22, s22, 0x8000
	s_addc_u32 s23, s23, 0
	global_load_dwordx4 v[122:125], v140, s[24:25]
	global_load_dwordx4 v[144:147], v141, s[46:47]
	global_load_dwordx4 v[166:169], v141, s[46:47] offset:16
	global_load_dwordx4 v[170:173], v140, s[24:25] offset:256
	global_load_dwordx4 v[118:121], v141, s[46:47] offset:512
	global_load_dwordx4 v[114:117], v141, s[46:47] offset:528
	s_add_u32 s24, s24, 0x78000
	s_addc_u32 s25, s25, 0
	s_add_u32 s46, s46, 0x50000
	s_addc_u32 s47, s47, 0
	s_waitcnt vmcnt(17)
	v_lshlrev_b32_e32 v148, 16, v174
	v_and_b32_e32 v149, 0xffff0000, v174
	v_lshlrev_b32_e32 v210, 16, v175
	v_and_b32_e32 v211, 0xffff0000, v175
	v_lshlrev_b32_e32 v212, 16, v176
	v_and_b32_e32 v213, 0xffff0000, v176
	v_lshlrev_b32_e32 v214, 16, v177
	v_and_b32_e32 v215, 0xffff0000, v177
	v_pk_mul_f32 v[110:111], v[110:111], v[148:149]
	v_pk_mul_f32 v[112:113], v[112:113], v[210:211]
	v_pk_mul_f32 v[106:107], v[106:107], v[212:213]
	v_pk_mul_f32 v[108:109], v[108:109], v[214:215]
	v_pk_add_f32 v[110:111], v[110:111], v[178:179]
	v_pk_add_f32 v[112:113], v[112:113], v[180:181]
	v_pk_add_f32 v[106:107], v[106:107], v[182:183]
	v_pk_add_f32 v[108:109], v[108:109], v[184:185]
	v_cvt_pk_bf16_f32 v174, v110, v111
	v_cvt_pk_bf16_f32 v175, v112, v113
	v_cvt_pk_bf16_f32 v176, v106, v107
	v_cvt_pk_bf16_f32 v177, v108, v109
	global_store_dwordx4 v142, v[174:177], s[22:23]
	global_load_dwordx4 v[162:165], v140, s[24:25]
	global_load_dwordx4 v[178:181], v141, s[46:47]
	global_load_dwordx4 v[182:185], v141, s[46:47] offset:16
	global_load_dwordx4 v[110:113], v140, s[24:25] offset:256
	global_load_dwordx4 v[106:109], v141, s[46:47] offset:512
	global_load_dwordx4 v[174:177], v141, s[46:47] offset:528
	s_add_u32 s24, s24, 0x18000
	s_addc_u32 s25, s25, 0
	s_add_u32 s46, s46, 0x10000
	s_addc_u32 s47, s47, 0
	s_waitcnt vmcnt(21)
; __device__ __forceinline__ unsigned cvt_pk_bf16(float lo, float hi) { f32x2 v = {lo, hi}; bf16x2_t b = __builtin_convertvector(v, bf16x2_t); return __builtin_bit_cast(unsigned, b); }
; __device__ __forceinline__ float bf_lo(unsigned w) { return __uint_as_float(w << 16); }
; __device__ __forceinline__ float bf_hi(unsigned w) { return __uint_as_float(w & 0xffff0000u); }
;     __device__ __forceinline__ void operator()(ACC_T, const Unit& u, int wr, int wc, int fr, int fq) const {
;     ...
;             for (int m = 0; m < 4; ++m) { const size_t row = (size_t)(row0 + ai * HALF + m * 16);
; #pragma unroll
;                 for (int bj = 0; bj < 2; ++bj) {
;                     const u32x4 gw = *(const u32x4*)(Gt + row * GW + u.z * DM + col0 + bj * HALF);
;                     f32x4 v0 = acc[ai][bj][m][0], v1 = acc[ai][bj][m][1];
;                     v0[0] *= bf_lo(gw.x); v0[1] *= bf_hi(gw.x); v0[2] *= bf_lo(gw.y); v0[3] *= bf_hi(gw.y);
;                     v1[0] *= bf_lo(gw.z); v1[1] *= bf_hi(gw.z); v1[2] *= bf_lo(gw.w); v1[3] *= bf_hi(gw.w);
;                     float* mp = M32 + (size_t)u.pm * (SLOTB / 4) + (row - (size_t)u.pm * BM) * DM + col0 + bj * HALF;
;                     if (u.z > 0) { v0 += *(const f32x4*)mp; v1 += *(const f32x4*)(mp + 4); }
;                     if (u.z < 2) { *(f32x4*)mp = v0; *(f32x4*)(mp + 4) = v1; }
;                     else { u32x4 w; w.x = cvt_pk_bf16(v0[0], v0[1]); w.y = cvt_pk_bf16(v0[2], v0[3]); w.z = cvt_pk_bf16(v1[0], v1[1]); w.w = cvt_pk_bf16(v1[2], v1[3]);
;                         *(u32x4*)(MG + row * DM + col0 + bj * HALF) = w; } } }
	v_lshlrev_b32_e32 v148, 16, v186
	v_and_b32_e32 v149, 0xffff0000, v186
	v_lshlrev_b32_e32 v210, 16, v187
	v_and_b32_e32 v211, 0xffff0000, v187
	v_lshlrev_b32_e32 v212, 16, v188
	v_and_b32_e32 v213, 0xffff0000, v188
	v_lshlrev_b32_e32 v214, 16, v189
	v_and_b32_e32 v215, 0xffff0000, v189
	v_pk_mul_f32 v[102:103], v[102:103], v[148:149]
	v_pk_mul_f32 v[104:105], v[104:105], v[210:211]
	v_pk_mul_f32 v[98:99], v[98:99], v[212:213]
	v_pk_mul_f32 v[100:101], v[100:101], v[214:215]
	v_pk_add_f32 v[102:103], v[102:103], v[190:191]
	v_pk_add_f32 v[104:105], v[104:105], v[192:193]
	v_pk_add_f32 v[98:99], v[98:99], v[194:195]
	v_pk_add_f32 v[100:101], v[100:101], v[196:197]
	v_cvt_pk_bf16_f32 v186, v102, v103
	v_cvt_pk_bf16_f32 v187, v104, v105
	v_cvt_pk_bf16_f32 v188, v98, v99
	v_cvt_pk_bf16_f32 v189, v100, v101
	global_store_dwordx4 v142, v[186:189], s[22:23] offset:256
	s_add_u32 s22, s22, 0x8000
	s_addc_u32 s23, s23, 0
	global_load_dwordx4 v[190:193], v140, s[24:25]
	global_load_dwordx4 v[194:197], v141, s[46:47]
	global_load_dwordx4 v[102:105], v141, s[46:47] offset:16
	s_waitcnt vmcnt(22)
	v_lshlrev_b32_e32 v148, 16, v198
	v_and_b32_e32 v149, 0xffff0000, v198
	v_lshlrev_b32_e32 v210, 16, v199
	v_and_b32_e32 v211, 0xffff0000, v199
	v_lshlrev_b32_e32 v212, 16, v200
	v_and_b32_e32 v213, 0xffff0000, v200
	v_lshlrev_b32_e32 v214, 16, v201
	v_and_b32_e32 v215, 0xffff0000, v201
	v_pk_mul_f32 v[94:95], v[94:95], v[148:149]
	v_pk_mul_f32 v[96:97], v[96:97], v[210:211]
	v_pk_mul_f32 v[90:91], v[90:91], v[212:213]
	v_pk_mul_f32 v[92:93], v[92:93], v[214:215]
	v_pk_add_f32 v[94:95], v[94:95], v[202:203]
	v_pk_add_f32 v[96:97], v[96:97], v[204:205]
	v_pk_add_f32 v[90:91], v[90:91], v[206:207]
	v_pk_add_f32 v[92:93], v[92:93], v[208:209]
	v_cvt_pk_bf16_f32 v198, v94, v95
	v_cvt_pk_bf16_f32 v199, v96, v97
	v_cvt_pk_bf16_f32 v200, v90, v91
	v_cvt_pk_bf16_f32 v201, v92, v93
	global_store_dwordx4 v142, v[198:201], s[22:23]
	global_load_dwordx4 v[98:101], v140, s[24:25] offset:256
	global_load_dwordx4 v[186:189], v141, s[46:47] offset:512
	global_load_dwordx4 v[202:205], v141, s[46:47] offset:528
	s_add_u32 s24, s24, 0x18000
	s_addc_u32 s25, s25, 0
	s_add_u32 s46, s46, 0x10000
	s_addc_u32 s47, s47, 0
	global_load_dwordx4 v[206:209], v140, s[24:25]
	global_load_dwordx4 v[94:97], v141, s[46:47]
	global_load_dwordx4 v[90:93], v141, s[46:47] offset:16
	s_waitcnt vmcnt(25)
	v_lshlrev_b32_e32 v148, 16, v154
	v_and_b32_e32 v149, 0xffff0000, v154
	v_lshlrev_b32_e32 v210, 16, v155
	v_and_b32_e32 v211, 0xffff0000, v155
	v_lshlrev_b32_e32 v212, 16, v156
	v_and_b32_e32 v213, 0xffff0000, v156
	v_lshlrev_b32_e32 v214, 16, v157
	v_and_b32_e32 v215, 0xffff0000, v157
	v_pk_mul_f32 v[86:87], v[86:87], v[148:149]
	v_pk_mul_f32 v[88:89], v[88:89], v[210:211]
	v_pk_mul_f32 v[82:83], v[82:83], v[212:213]
	v_pk_mul_f32 v[84:85], v[84:85], v[214:215]
	v_pk_add_f32 v[86:87], v[86:87], v[158:159]
	v_pk_add_f32 v[88:89], v[88:89], v[160:161]
	v_pk_add_f32 v[82:83], v[82:83], v[126:127]
	v_pk_add_f32 v[84:85], v[84:85], v[128:129]
	v_cvt_pk_bf16_f32 v154, v86, v87
	v_cvt_pk_bf16_f32 v155, v88, v89
	v_cvt_pk_bf16_f32 v156, v82, v83
	v_cvt_pk_bf16_f32 v157, v84, v85
	global_store_dwordx4 v142, v[154:157], s[22:23] offset:256
	s_add_u32 s22, s22, 0x8000
	s_addc_u32 s23, s23, 0
	global_load_dwordx4 v[198:201], v140, s[24:25] offset:256
	global_load_dwordx4 v[158:161], v141, s[46:47] offset:512
	global_load_dwordx4 v[126:129], v141, s[46:47] offset:528
	s_add_u32 s24, s24, 0x18000
	s_addc_u32 s25, s25, 0
	s_add_u32 s46, s46, 0x10000
	s_addc_u32 s47, s47, 0
	global_load_dwordx4 v[86:89], v140, s[24:25]
	global_load_dwordx4 v[82:85], v141, s[46:47]
	global_load_dwordx4 v[154:157], v141, s[46:47] offset:16
	s_waitcnt vmcnt(28)
	v_lshlrev_b32_e32 v148, 16, v122
	v_and_b32_e32 v149, 0xffff0000, v122
	v_lshlrev_b32_e32 v210, 16, v123
	v_and_b32_e32 v211, 0xffff0000, v123
	v_lshlrev_b32_e32 v212, 16, v124
	v_and_b32_e32 v213, 0xffff0000, v124
	v_lshlrev_b32_e32 v214, 16, v125
	v_and_b32_e32 v215, 0xffff0000, v125
	v_pk_mul_f32 v[78:79], v[78:79], v[148:149]
	v_pk_mul_f32 v[80:81], v[80:81], v[210:211]
	v_pk_mul_f32 v[74:75], v[74:75], v[212:213]
	v_pk_mul_f32 v[76:77], v[76:77], v[214:215]
	v_pk_add_f32 v[78:79], v[78:79], v[144:145]
	v_pk_add_f32 v[80:81], v[80:81], v[146:147]
	v_pk_add_f32 v[74:75], v[74:75], v[166:167]
	v_pk_add_f32 v[76:77], v[76:77], v[168:169]
	v_cvt_pk_bf16_f32 v122, v78, v79
	v_cvt_pk_bf16_f32 v123, v80, v81
	v_cvt_pk_bf16_f32 v124, v74, v75
	v_cvt_pk_bf16_f32 v125, v76, v77
	global_store_dwordx4 v142, v[122:125], s[22:23]
	global_load_dwordx4 v[144:147], v140, s[24:25] offset:256
	global_load_dwordx4 v[166:169], v141, s[46:47] offset:512
	global_load_dwordx4 v[78:81], v141, s[46:47] offset:528
	s_waitcnt vmcnt(29)
	v_lshlrev_b32_e32 v148, 16, v170
	v_and_b32_e32 v149, 0xffff0000, v170
	v_lshlrev_b32_e32 v210, 16, v171
	v_and_b32_e32 v211, 0xffff0000, v171
	v_lshlrev_b32_e32 v212, 16, v172
	v_and_b32_e32 v213, 0xffff0000, v172
	v_lshlrev_b32_e32 v214, 16, v173
	v_and_b32_e32 v215, 0xffff0000, v173
	v_pk_mul_f32 v[70:71], v[70:71], v[148:149]
	v_pk_mul_f32 v[72:73], v[72:73], v[210:211]
	v_pk_mul_f32 v[66:67], v[66:67], v[212:213]
	v_pk_mul_f32 v[68:69], v[68:69], v[214:215]
	v_pk_add_f32 v[70:71], v[70:71], v[118:119]
	v_pk_add_f32 v[72:73], v[72:73], v[120:121]
	v_pk_add_f32 v[66:67], v[66:67], v[114:115]
	v_pk_add_f32 v[68:69], v[68:69], v[116:117]
	v_cvt_pk_bf16_f32 v170, v70, v71
	v_cvt_pk_bf16_f32 v171, v72, v73
	v_cvt_pk_bf16_f32 v172, v66, v67
	v_cvt_pk_bf16_f32 v173, v68, v69
	global_store_dwordx4 v142, v[170:173], s[22:23] offset:256
	s_add_u32 s22, s22, 0x28000
	s_addc_u32 s23, s23, 0
	s_waitcnt vmcnt(26)
; __device__ __forceinline__ unsigned cvt_pk_bf16(float lo, float hi) { f32x2 v = {lo, hi}; bf16x2_t b = __builtin_convertvector(v, bf16x2_t); return __builtin_bit_cast(unsigned, b); }
; __device__ __forceinline__ float bf_lo(unsigned w) { return __uint_as_float(w << 16); }
; __device__ __forceinline__ float bf_hi(unsigned w) { return __uint_as_float(w & 0xffff0000u); }
;     __device__ __forceinline__ void operator()(ACC_T, const Unit& u, int wr, int wc, int fr, int fq) const {
;     ...
;             for (int m = 0; m < 4; ++m) { const size_t row = (size_t)(row0 + ai * HALF + m * 16);
; #pragma unroll
;                 for (int bj = 0; bj < 2; ++bj) {
;                     const u32x4 gw = *(const u32x4*)(Gt + row * GW + u.z * DM + col0 + bj * HALF);
;                     f32x4 v0 = acc[ai][bj][m][0], v1 = acc[ai][bj][m][1];
;                     v0[0] *= bf_lo(gw.x); v0[1] *= bf_hi(gw.x); v0[2] *= bf_lo(gw.y); v0[3] *= bf_hi(gw.y);
;                     v1[0] *= bf_lo(gw.z); v1[1] *= bf_hi(gw.z); v1[2] *= bf_lo(gw.w); v1[3] *= bf_hi(gw.w);
;                     float* mp = M32 + (size_t)u.pm * (SLOTB / 4) + (row - (size_t)u.pm * BM) * DM + col0 + bj * HALF;
;                     if (u.z > 0) { v0 += *(const f32x4*)mp; v1 += *(const f32x4*)(mp + 4); }
;                     if (u.z < 2) { *(f32x4*)mp = v0; *(f32x4*)(mp + 4) = v1; }
;                     else { u32x4 w; w.x = cvt_pk_bf16(v0[0], v0[1]); w.y = cvt_pk_bf16(v0[2], v0[3]); w.z = cvt_pk_bf16(v1[0], v1[1]); w.w = cvt_pk_bf16(v1[2], v1[3]);
;                         *(u32x4*)(MG + row * DM + col0 + bj * HALF) = w; } } }
	v_lshlrev_b32_e32 v148, 16, v162
	v_and_b32_e32 v149, 0xffff0000, v162
	v_lshlrev_b32_e32 v210, 16, v163
	v_and_b32_e32 v211, 0xffff0000, v163
	v_lshlrev_b32_e32 v212, 16, v164
	v_and_b32_e32 v213, 0xffff0000, v164
	v_lshlrev_b32_e32 v214, 16, v165
	v_and_b32_e32 v215, 0xffff0000, v165
	v_pk_mul_f32 v[62:63], v[62:63], v[148:149]
	v_pk_mul_f32 v[64:65], v[64:65], v[210:211]
	v_pk_mul_f32 v[58:59], v[58:59], v[212:213]
	v_pk_mul_f32 v[60:61], v[60:61], v[214:215]
	v_pk_add_f32 v[62:63], v[62:63], v[178:179]
	v_pk_add_f32 v[64:65], v[64:65], v[180:181]
	v_pk_add_f32 v[58:59], v[58:59], v[182:183]
	v_pk_add_f32 v[60:61], v[60:61], v[184:185]
	v_cvt_pk_bf16_f32 v162, v62, v63
	v_cvt_pk_bf16_f32 v163, v64, v65
	v_cvt_pk_bf16_f32 v164, v58, v59
	v_cvt_pk_bf16_f32 v165, v60, v61
	global_store_dwordx4 v142, v[162:165], s[22:23]
	s_waitcnt vmcnt(24)
	v_lshlrev_b32_e32 v148, 16, v110
	v_and_b32_e32 v149, 0xffff0000, v110
	v_lshlrev_b32_e32 v210, 16, v111
	v_and_b32_e32 v211, 0xffff0000, v111
	v_lshlrev_b32_e32 v212, 16, v112
	v_and_b32_e32 v213, 0xffff0000, v112
	v_lshlrev_b32_e32 v214, 16, v113
	v_and_b32_e32 v215, 0xffff0000, v113
	v_pk_mul_f32 v[54:55], v[54:55], v[148:149]
	v_pk_mul_f32 v[56:57], v[56:57], v[210:211]
	v_pk_mul_f32 v[50:51], v[50:51], v[212:213]
	v_pk_mul_f32 v[52:53], v[52:53], v[214:215]
	v_pk_add_f32 v[54:55], v[54:55], v[106:107]
	v_pk_add_f32 v[56:57], v[56:57], v[108:109]
	v_pk_add_f32 v[50:51], v[50:51], v[174:175]
	v_pk_add_f32 v[52:53], v[52:53], v[176:177]
	v_cvt_pk_bf16_f32 v110, v54, v55
	v_cvt_pk_bf16_f32 v111, v56, v57
	v_cvt_pk_bf16_f32 v112, v50, v51
	v_cvt_pk_bf16_f32 v113, v52, v53
	global_store_dwordx4 v142, v[110:113], s[22:23] offset:256
	s_add_u32 s22, s22, 0x8000
	s_addc_u32 s23, s23, 0
	s_waitcnt vmcnt(21)
	v_lshlrev_b32_e32 v148, 16, v190
	v_and_b32_e32 v149, 0xffff0000, v190
	v_lshlrev_b32_e32 v210, 16, v191
	v_and_b32_e32 v211, 0xffff0000, v191
	v_lshlrev_b32_e32 v212, 16, v192
	v_and_b32_e32 v213, 0xffff0000, v192
	v_lshlrev_b32_e32 v214, 16, v193
	v_and_b32_e32 v215, 0xffff0000, v193
	v_pk_mul_f32 v[46:47], v[46:47], v[148:149]
	v_pk_mul_f32 v[48:49], v[48:49], v[210:211]
	v_pk_mul_f32 v[42:43], v[42:43], v[212:213]
	v_pk_mul_f32 v[44:45], v[44:45], v[214:215]
	v_pk_add_f32 v[46:47], v[46:47], v[194:195]
	v_pk_add_f32 v[48:49], v[48:49], v[196:197]
	v_pk_add_f32 v[42:43], v[42:43], v[102:103]
	v_pk_add_f32 v[44:45], v[44:45], v[104:105]
	v_cvt_pk_bf16_f32 v190, v46, v47
	v_cvt_pk_bf16_f32 v191, v48, v49
	v_cvt_pk_bf16_f32 v192, v42, v43
	v_cvt_pk_bf16_f32 v193, v44, v45
	global_store_dwordx4 v142, v[190:193], s[22:23]
	s_waitcnt vmcnt(18)
	v_lshlrev_b32_e32 v148, 16, v98
	v_and_b32_e32 v149, 0xffff0000, v98
	v_lshlrev_b32_e32 v210, 16, v99
	v_and_b32_e32 v211, 0xffff0000, v99
	v_lshlrev_b32_e32 v212, 16, v100
	v_and_b32_e32 v213, 0xffff0000, v100
	v_lshlrev_b32_e32 v214, 16, v101
	v_and_b32_e32 v215, 0xffff0000, v101
	v_pk_mul_f32 v[38:39], v[38:39], v[148:149]
	v_pk_mul_f32 v[40:41], v[40:41], v[210:211]
	v_pk_mul_f32 v[34:35], v[34:35], v[212:213]
	v_pk_mul_f32 v[36:37], v[36:37], v[214:215]
	v_pk_add_f32 v[38:39], v[38:39], v[186:187]
	v_pk_add_f32 v[40:41], v[40:41], v[188:189]
	v_pk_add_f32 v[34:35], v[34:35], v[202:203]
	v_pk_add_f32 v[36:37], v[36:37], v[204:205]
	v_cvt_pk_bf16_f32 v98, v38, v39
	v_cvt_pk_bf16_f32 v99, v40, v41
	v_cvt_pk_bf16_f32 v100, v34, v35
	v_cvt_pk_bf16_f32 v101, v36, v37
	global_store_dwordx4 v142, v[98:101], s[22:23] offset:256
	s_add_u32 s22, s22, 0x8000
	s_addc_u32 s23, s23, 0
	s_waitcnt vmcnt(16)
	v_lshlrev_b32_e32 v148, 16, v206
	v_and_b32_e32 v149, 0xffff0000, v206
	v_lshlrev_b32_e32 v210, 16, v207
	v_and_b32_e32 v211, 0xffff0000, v207
	v_lshlrev_b32_e32 v212, 16, v208
	v_and_b32_e32 v213, 0xffff0000, v208
	v_lshlrev_b32_e32 v214, 16, v209
	v_and_b32_e32 v215, 0xffff0000, v209
	v_pk_mul_f32 v[30:31], v[30:31], v[148:149]
	v_pk_mul_f32 v[32:33], v[32:33], v[210:211]
	v_pk_mul_f32 v[26:27], v[26:27], v[212:213]
	v_pk_mul_f32 v[28:29], v[28:29], v[214:215]
	v_pk_add_f32 v[30:31], v[30:31], v[94:95]
	v_pk_add_f32 v[32:33], v[32:33], v[96:97]
	v_pk_add_f32 v[26:27], v[26:27], v[90:91]
	v_pk_add_f32 v[28:29], v[28:29], v[92:93]
	v_cvt_pk_bf16_f32 v206, v30, v31
	v_cvt_pk_bf16_f32 v207, v32, v33
	v_cvt_pk_bf16_f32 v208, v26, v27
	v_cvt_pk_bf16_f32 v209, v28, v29
	global_store_dwordx4 v142, v[206:209], s[22:23]
	s_waitcnt vmcnt(13)
	v_lshlrev_b32_e32 v148, 16, v198
	v_and_b32_e32 v149, 0xffff0000, v198
	v_lshlrev_b32_e32 v210, 16, v199
	v_and_b32_e32 v211, 0xffff0000, v199
	v_lshlrev_b32_e32 v212, 16, v200
	v_and_b32_e32 v213, 0xffff0000, v200
	v_lshlrev_b32_e32 v214, 16, v201
	v_and_b32_e32 v215, 0xffff0000, v201
	v_pk_mul_f32 v[22:23], v[22:23], v[148:149]
	v_pk_mul_f32 v[24:25], v[24:25], v[210:211]
	v_pk_mul_f32 v[18:19], v[18:19], v[212:213]
	v_pk_mul_f32 v[20:21], v[20:21], v[214:215]
	v_pk_add_f32 v[22:23], v[22:23], v[158:159]
	v_pk_add_f32 v[24:25], v[24:25], v[160:161]
	v_pk_add_f32 v[18:19], v[18:19], v[126:127]
	v_pk_add_f32 v[20:21], v[20:21], v[128:129]
	v_cvt_pk_bf16_f32 v198, v22, v23
	v_cvt_pk_bf16_f32 v199, v24, v25
	v_cvt_pk_bf16_f32 v200, v18, v19
	v_cvt_pk_bf16_f32 v201, v20, v21
	global_store_dwordx4 v142, v[198:201], s[22:23] offset:256
	s_add_u32 s22, s22, 0x8000
	s_addc_u32 s23, s23, 0
	s_waitcnt vmcnt(11)
	v_lshlrev_b32_e32 v148, 16, v86
	v_and_b32_e32 v149, 0xffff0000, v86
	v_lshlrev_b32_e32 v210, 16, v87
	v_and_b32_e32 v211, 0xffff0000, v87
	v_lshlrev_b32_e32 v212, 16, v88
	v_and_b32_e32 v213, 0xffff0000, v88
	v_lshlrev_b32_e32 v214, 16, v89
	v_and_b32_e32 v215, 0xffff0000, v89
	v_pk_mul_f32 v[14:15], v[14:15], v[148:149]
	v_pk_mul_f32 v[16:17], v[16:17], v[210:211]
	v_pk_mul_f32 v[10:11], v[10:11], v[212:213]
	v_pk_mul_f32 v[12:13], v[12:13], v[214:215]
	v_pk_add_f32 v[14:15], v[14:15], v[82:83]
	v_pk_add_f32 v[16:17], v[16:17], v[84:85]
	v_pk_add_f32 v[10:11], v[10:11], v[154:155]
	v_pk_add_f32 v[12:13], v[12:13], v[156:157]
	v_cvt_pk_bf16_f32 v86, v14, v15
	v_cvt_pk_bf16_f32 v87, v16, v17
	v_cvt_pk_bf16_f32 v88, v10, v11
	v_cvt_pk_bf16_f32 v89, v12, v13
	global_store_dwordx4 v142, v[86:89], s[22:23]
	s_waitcnt vmcnt(8)
	v_lshlrev_b32_e32 v148, 16, v144
	v_and_b32_e32 v149, 0xffff0000, v144
	v_lshlrev_b32_e32 v210, 16, v145
	v_and_b32_e32 v211, 0xffff0000, v145
	v_lshlrev_b32_e32 v212, 16, v146
	v_and_b32_e32 v213, 0xffff0000, v146
	v_lshlrev_b32_e32 v214, 16, v147
	v_and_b32_e32 v215, 0xffff0000, v147
	v_pk_mul_f32 v[6:7], v[6:7], v[148:149]
	v_pk_mul_f32 v[8:9], v[8:9], v[210:211]
	v_pk_mul_f32 v[2:3], v[2:3], v[212:213]
	v_pk_mul_f32 v[4:5], v[4:5], v[214:215]
	v_pk_add_f32 v[6:7], v[6:7], v[166:167]
	v_pk_add_f32 v[8:9], v[8:9], v[168:169]
	v_pk_add_f32 v[2:3], v[2:3], v[78:79]
	v_pk_add_f32 v[4:5], v[4:5], v[80:81]
	v_cvt_pk_bf16_f32 v144, v6, v7
	v_cvt_pk_bf16_f32 v145, v8, v9
	v_cvt_pk_bf16_f32 v146, v2, v3
	v_cvt_pk_bf16_f32 v147, v4, v5
	global_store_dwordx4 v142, v[144:147], s[22:23] offset:256
	s_branch .Lbr_done
; __device__ __forceinline__ float bf_lo(unsigned w) { return __uint_as_float(w << 16); }
; __device__ __forceinline__ float bf_hi(unsigned w) { return __uint_as_float(w & 0xffff0000u); }
;     __device__ __forceinline__ void operator()(ACC_T, const Unit& u, int wr, int wc, int fr, int fq) const {
;     ...
;                     const u32x4 gw = *(const u32x4*)(Gt + row * GW + u.z * DM + col0 + bj * HALF);
;                     f32x4 v0 = acc[ai][bj][m][0], v1 = acc[ai][bj][m][1];
;                     v0[0] *= bf_lo(gw.x); v0[1] *= bf_hi(gw.x); v0[2] *= bf_lo(gw.y); v0[3] *= bf_hi(gw.y);
;                     v1[0] *= bf_lo(gw.z); v1[1] *= bf_hi(gw.z); v1[2] *= bf_lo(gw.w); v1[3] *= bf_hi(gw.w);
;                     float* mp = M32 + (size_t)u.pm * (SLOTB / 4) + (row - (size_t)u.pm * BM) * DM + col0 + bj * HALF;
;                     if (u.z > 0) { v0 += *(const f32x4*)mp; v1 += *(const f32x4*)(mp + 4); }
;                     if (u.z < 2) { *(f32x4*)mp = v0; *(f32x4*)(mp + 4) = v1; }
.Lbr_z0:
	global_load_dwordx4 v[144:147], v140, s[24:25]
	global_load_dwordx4 v[154:157], v140, s[24:25] offset:256
	s_add_u32 s24, s24, 0x18000
	s_addc_u32 s25, s25, 0
	global_load_dwordx4 v[158:161], v140, s[24:25]
	global_load_dwordx4 v[162:165], v140, s[24:25] offset:256
	s_add_u32 s24, s24, 0x18000
	s_addc_u32 s25, s25, 0
	global_load_dwordx4 v[166:169], v140, s[24:25]
	global_load_dwordx4 v[170:173], v140, s[24:25] offset:256
	s_add_u32 s24, s24, 0x18000
	s_addc_u32 s25, s25, 0
	global_load_dwordx4 v[174:177], v140, s[24:25]
	global_load_dwordx4 v[178:181], v140, s[24:25] offset:256
	s_add_u32 s24, s24, 0x78000
	s_addc_u32 s25, s25, 0
	global_load_dwordx4 v[182:185], v140, s[24:25]
	global_load_dwordx4 v[186:189], v140, s[24:25] offset:256
	s_add_u32 s24, s24, 0x18000
	s_addc_u32 s25, s25, 0
	global_load_dwordx4 v[190:193], v140, s[24:25]
	global_load_dwordx4 v[194:197], v140, s[24:25] offset:256
	s_add_u32 s24, s24, 0x18000
	s_addc_u32 s25, s25, 0
	global_load_dwordx4 v[198:201], v140, s[24:25]
	s_waitcnt vmcnt(12)
	v_lshlrev_b32_e32 v148, 16, v144
	v_and_b32_e32 v149, 0xffff0000, v144
	v_lshlrev_b32_e32 v210, 16, v145
	v_and_b32_e32 v211, 0xffff0000, v145
	v_lshlrev_b32_e32 v212, 16, v146
	v_and_b32_e32 v213, 0xffff0000, v146
	v_lshlrev_b32_e32 v214, 16, v147
	v_and_b32_e32 v215, 0xffff0000, v147
	v_pk_mul_f32 v[126:127], v[126:127], v[148:149]
	v_pk_mul_f32 v[128:129], v[128:129], v[210:211]
	v_pk_mul_f32 v[122:123], v[122:123], v[212:213]
	v_pk_mul_f32 v[124:125], v[124:125], v[214:215]
	global_store_dwordx4 v141, v[126:129], s[48:49]
	global_store_dwordx4 v141, v[122:125], s[48:49] offset:16
	global_load_dwordx4 v[202:205], v140, s[24:25] offset:256
	s_add_u32 s24, s24, 0x18000
	s_addc_u32 s25, s25, 0
	s_waitcnt vmcnt(14)
	v_lshlrev_b32_e32 v148, 16, v154
	v_and_b32_e32 v149, 0xffff0000, v154
	v_lshlrev_b32_e32 v210, 16, v155
	v_and_b32_e32 v211, 0xffff0000, v155
	v_lshlrev_b32_e32 v212, 16, v156
	v_and_b32_e32 v213, 0xffff0000, v156
	v_lshlrev_b32_e32 v214, 16, v157
	v_and_b32_e32 v215, 0xffff0000, v157
	v_pk_mul_f32 v[118:119], v[118:119], v[148:149]
	v_pk_mul_f32 v[120:121], v[120:121], v[210:211]
	v_pk_mul_f32 v[114:115], v[114:115], v[212:213]
	v_pk_mul_f32 v[116:117], v[116:117], v[214:215]
	global_store_dwordx4 v141, v[118:121], s[48:49] offset:512
	global_store_dwordx4 v141, v[114:117], s[48:49] offset:528
	s_add_u32 s48, s48, 0x10000
	s_addc_u32 s49, s49, 0
	global_load_dwordx4 v[206:209], v140, s[24:25]
	s_waitcnt vmcnt(16)
	v_lshlrev_b32_e32 v148, 16, v158
	v_and_b32_e32 v149, 0xffff0000, v158
	v_lshlrev_b32_e32 v210, 16, v159
	v_and_b32_e32 v211, 0xffff0000, v159
	v_lshlrev_b32_e32 v212, 16, v160
	v_and_b32_e32 v213, 0xffff0000, v160
	v_lshlrev_b32_e32 v214, 16, v161
	v_and_b32_e32 v215, 0xffff0000, v161
	v_pk_mul_f32 v[110:111], v[110:111], v[148:149]
	v_pk_mul_f32 v[112:113], v[112:113], v[210:211]
	v_pk_mul_f32 v[106:107], v[106:107], v[212:213]
	v_pk_mul_f32 v[108:109], v[108:109], v[214:215]
	global_store_dwordx4 v141, v[110:113], s[48:49]
	global_store_dwordx4 v141, v[106:109], s[48:49] offset:16
	global_load_dwordx4 v[144:147], v140, s[24:25] offset:256
	s_waitcnt vmcnt(18)
	v_lshlrev_b32_e32 v148, 16, v162
	v_and_b32_e32 v149, 0xffff0000, v162
	v_lshlrev_b32_e32 v210, 16, v163
	v_and_b32_e32 v211, 0xffff0000, v163
	v_lshlrev_b32_e32 v212, 16, v164
	v_and_b32_e32 v213, 0xffff0000, v164
	v_lshlrev_b32_e32 v214, 16, v165
	v_and_b32_e32 v215, 0xffff0000, v165
	v_pk_mul_f32 v[102:103], v[102:103], v[148:149]
	v_pk_mul_f32 v[104:105], v[104:105], v[210:211]
	v_pk_mul_f32 v[98:99], v[98:99], v[212:213]
	v_pk_mul_f32 v[100:101], v[100:101], v[214:215]
	global_store_dwordx4 v141, v[102:105], s[48:49] offset:512
	global_store_dwordx4 v141, v[98:101], s[48:49] offset:528
	s_add_u32 s48, s48, 0x10000
	s_addc_u32 s49, s49, 0
	s_waitcnt vmcnt(19)
	v_lshlrev_b32_e32 v148, 16, v166
	v_and_b32_e32 v149, 0xffff0000, v166
	v_lshlrev_b32_e32 v210, 16, v167
	v_and_b32_e32 v211, 0xffff0000, v167
	v_lshlrev_b32_e32 v212, 16, v168
	v_and_b32_e32 v213, 0xffff0000, v168
	v_lshlrev_b32_e32 v214, 16, v169
	v_and_b32_e32 v215, 0xffff0000, v169
	v_pk_mul_f32 v[94:95], v[94:95], v[148:149]
	v_pk_mul_f32 v[96:97], v[96:97], v[210:211]
	v_pk_mul_f32 v[90:91], v[90:91], v[212:213]
	v_pk_mul_f32 v[92:93], v[92:93], v[214:215]
	global_store_dwordx4 v141, v[94:97], s[48:49]
	global_store_dwordx4 v141, v[90:93], s[48:49] offset:16
	s_waitcnt vmcnt(20)
	v_lshlrev_b32_e32 v148, 16, v170
	v_and_b32_e32 v149, 0xffff0000, v170
	v_lshlrev_b32_e32 v210, 16, v171
	v_and_b32_e32 v211, 0xffff0000, v171
	v_lshlrev_b32_e32 v212, 16, v172
	v_and_b32_e32 v213, 0xffff0000, v172
	v_lshlrev_b32_e32 v214, 16, v173
	v_and_b32_e32 v215, 0xffff0000, v173
	v_pk_mul_f32 v[86:87], v[86:87], v[148:149]
	v_pk_mul_f32 v[88:89], v[88:89], v[210:211]
	v_pk_mul_f32 v[82:83], v[82:83], v[212:213]
	v_pk_mul_f32 v[84:85], v[84:85], v[214:215]
	global_store_dwordx4 v141, v[86:89], s[48:49] offset:512
	global_store_dwordx4 v141, v[82:85], s[48:49] offset:528
	s_add_u32 s48, s48, 0x10000
	s_addc_u32 s49, s49, 0
	s_waitcnt vmcnt(21)
	v_lshlrev_b32_e32 v148, 16, v174
	v_and_b32_e32 v149, 0xffff0000, v174
	v_lshlrev_b32_e32 v210, 16, v175
	v_and_b32_e32 v211, 0xffff0000, v175
	v_lshlrev_b32_e32 v212, 16, v176
	v_and_b32_e32 v213, 0xffff0000, v176
	v_lshlrev_b32_e32 v214, 16, v177
	v_and_b32_e32 v215, 0xffff0000, v177
	v_pk_mul_f32 v[78:79], v[78:79], v[148:149]
	v_pk_mul_f32 v[80:81], v[80:81], v[210:211]
	v_pk_mul_f32 v[74:75], v[74:75], v[212:213]
	v_pk_mul_f32 v[76:77], v[76:77], v[214:215]
	global_store_dwordx4 v141, v[78:81], s[48:49]
	global_store_dwordx4 v141, v[74:77], s[48:49] offset:16
	s_waitcnt vmcnt(22)
; __device__ __forceinline__ float bf_lo(unsigned w) { return __uint_as_float(w << 16); }
; __device__ __forceinline__ float bf_hi(unsigned w) { return __uint_as_float(w & 0xffff0000u); }
;     __device__ __forceinline__ void operator()(ACC_T, const Unit& u, int wr, int wc, int fr, int fq) const {
;     ...
;                     const u32x4 gw = *(const u32x4*)(Gt + row * GW + u.z * DM + col0 + bj * HALF);
;                     f32x4 v0 = acc[ai][bj][m][0], v1 = acc[ai][bj][m][1];
;                     v0[0] *= bf_lo(gw.x); v0[1] *= bf_hi(gw.x); v0[2] *= bf_lo(gw.y); v0[3] *= bf_hi(gw.y);
;                     v1[0] *= bf_lo(gw.z); v1[1] *= bf_hi(gw.z); v1[2] *= bf_lo(gw.w); v1[3] *= bf_hi(gw.w);
;                     float* mp = M32 + (size_t)u.pm * (SLOTB / 4) + (row - (size_t)u.pm * BM) * DM + col0 + bj * HALF;
;                     if (u.z > 0) { v0 += *(const f32x4*)mp; v1 += *(const f32x4*)(mp + 4); }
;                     if (u.z < 2) { *(f32x4*)mp = v0; *(f32x4*)(mp + 4) = v1; }
	v_lshlrev_b32_e32 v148, 16, v178
	v_and_b32_e32 v149, 0xffff0000, v178
	v_lshlrev_b32_e32 v210, 16, v179
	v_and_b32_e32 v211, 0xffff0000, v179
	v_lshlrev_b32_e32 v212, 16, v180
	v_and_b32_e32 v213, 0xffff0000, v180
	v_lshlrev_b32_e32 v214, 16, v181
	v_and_b32_e32 v215, 0xffff0000, v181
	v_pk_mul_f32 v[70:71], v[70:71], v[148:149]
	v_pk_mul_f32 v[72:73], v[72:73], v[210:211]
	v_pk_mul_f32 v[66:67], v[66:67], v[212:213]
	v_pk_mul_f32 v[68:69], v[68:69], v[214:215]
	global_store_dwordx4 v141, v[70:73], s[48:49] offset:512
	global_store_dwordx4 v141, v[66:69], s[48:49] offset:528
	s_add_u32 s48, s48, 0x50000
	s_addc_u32 s49, s49, 0
	s_waitcnt vmcnt(23)
	v_lshlrev_b32_e32 v148, 16, v182
	v_and_b32_e32 v149, 0xffff0000, v182
	v_lshlrev_b32_e32 v210, 16, v183
	v_and_b32_e32 v211, 0xffff0000, v183
	v_lshlrev_b32_e32 v212, 16, v184
	v_and_b32_e32 v213, 0xffff0000, v184
	v_lshlrev_b32_e32 v214, 16, v185
	v_and_b32_e32 v215, 0xffff0000, v185
	v_pk_mul_f32 v[62:63], v[62:63], v[148:149]
	v_pk_mul_f32 v[64:65], v[64:65], v[210:211]
	v_pk_mul_f32 v[58:59], v[58:59], v[212:213]
	v_pk_mul_f32 v[60:61], v[60:61], v[214:215]
	global_store_dwordx4 v141, v[62:65], s[48:49]
	global_store_dwordx4 v141, v[58:61], s[48:49] offset:16
	s_waitcnt vmcnt(24)
	v_lshlrev_b32_e32 v148, 16, v186
	v_and_b32_e32 v149, 0xffff0000, v186
	v_lshlrev_b32_e32 v210, 16, v187
	v_and_b32_e32 v211, 0xffff0000, v187
	v_lshlrev_b32_e32 v212, 16, v188
	v_and_b32_e32 v213, 0xffff0000, v188
	v_lshlrev_b32_e32 v214, 16, v189
	v_and_b32_e32 v215, 0xffff0000, v189
	v_pk_mul_f32 v[54:55], v[54:55], v[148:149]
	v_pk_mul_f32 v[56:57], v[56:57], v[210:211]
	v_pk_mul_f32 v[50:51], v[50:51], v[212:213]
	v_pk_mul_f32 v[52:53], v[52:53], v[214:215]
	global_store_dwordx4 v141, v[54:57], s[48:49] offset:512
	global_store_dwordx4 v141, v[50:53], s[48:49] offset:528
	s_add_u32 s48, s48, 0x10000
	s_addc_u32 s49, s49, 0
	s_waitcnt vmcnt(25)
	v_lshlrev_b32_e32 v148, 16, v190
	v_and_b32_e32 v149, 0xffff0000, v190
	v_lshlrev_b32_e32 v210, 16, v191
	v_and_b32_e32 v211, 0xffff0000, v191
	v_lshlrev_b32_e32 v212, 16, v192
	v_and_b32_e32 v213, 0xffff0000, v192
	v_lshlrev_b32_e32 v214, 16, v193
	v_and_b32_e32 v215, 0xffff0000, v193
	v_pk_mul_f32 v[46:47], v[46:47], v[148:149]
	v_pk_mul_f32 v[48:49], v[48:49], v[210:211]
	v_pk_mul_f32 v[42:43], v[42:43], v[212:213]
	v_pk_mul_f32 v[44:45], v[44:45], v[214:215]
	global_store_dwordx4 v141, v[46:49], s[48:49]
	global_store_dwordx4 v141, v[42:45], s[48:49] offset:16
	s_waitcnt vmcnt(26)
	v_lshlrev_b32_e32 v148, 16, v194
	v_and_b32_e32 v149, 0xffff0000, v194
	v_lshlrev_b32_e32 v210, 16, v195
	v_and_b32_e32 v211, 0xffff0000, v195
	v_lshlrev_b32_e32 v212, 16, v196
	v_and_b32_e32 v213, 0xffff0000, v196
	v_lshlrev_b32_e32 v214, 16, v197
	v_and_b32_e32 v215, 0xffff0000, v197
	v_pk_mul_f32 v[38:39], v[38:39], v[148:149]
	v_pk_mul_f32 v[40:41], v[40:41], v[210:211]
	v_pk_mul_f32 v[34:35], v[34:35], v[212:213]
	v_pk_mul_f32 v[36:37], v[36:37], v[214:215]
	global_store_dwordx4 v141, v[38:41], s[48:49] offset:512
	global_store_dwordx4 v141, v[34:37], s[48:49] offset:528
	s_add_u32 s48, s48, 0x10000
	s_addc_u32 s49, s49, 0
	s_waitcnt vmcnt(27)
	v_lshlrev_b32_e32 v148, 16, v198
	v_and_b32_e32 v149, 0xffff0000, v198
	v_lshlrev_b32_e32 v210, 16, v199
	v_and_b32_e32 v211, 0xffff0000, v199
	v_lshlrev_b32_e32 v212, 16, v200
	v_and_b32_e32 v213, 0xffff0000, v200
	v_lshlrev_b32_e32 v214, 16, v201
	v_and_b32_e32 v215, 0xffff0000, v201
	v_pk_mul_f32 v[30:31], v[30:31], v[148:149]
	v_pk_mul_f32 v[32:33], v[32:33], v[210:211]
	v_pk_mul_f32 v[26:27], v[26:27], v[212:213]
	v_pk_mul_f32 v[28:29], v[28:29], v[214:215]
	global_store_dwordx4 v141, v[30:33], s[48:49]
	global_store_dwordx4 v141, v[26:29], s[48:49] offset:16
	s_waitcnt vmcnt(26)
	v_lshlrev_b32_e32 v148, 16, v202
	v_and_b32_e32 v149, 0xffff0000, v202
	v_lshlrev_b32_e32 v210, 16, v203
	v_and_b32_e32 v211, 0xffff0000, v203
	v_lshlrev_b32_e32 v212, 16, v204
	v_and_b32_e32 v213, 0xffff0000, v204
	v_lshlrev_b32_e32 v214, 16, v205
	v_and_b32_e32 v215, 0xffff0000, v205
	v_pk_mul_f32 v[22:23], v[22:23], v[148:149]
	v_pk_mul_f32 v[24:25], v[24:25], v[210:211]
	v_pk_mul_f32 v[18:19], v[18:19], v[212:213]
	v_pk_mul_f32 v[20:21], v[20:21], v[214:215]
	global_store_dwordx4 v141, v[22:25], s[48:49] offset:512
	global_store_dwordx4 v141, v[18:21], s[48:49] offset:528
	s_add_u32 s48, s48, 0x10000
	s_addc_u32 s49, s49, 0
	s_waitcnt vmcnt(25)
	v_lshlrev_b32_e32 v148, 16, v206
	v_and_b32_e32 v149, 0xffff0000, v206
	v_lshlrev_b32_e32 v210, 16, v207
	v_and_b32_e32 v211, 0xffff0000, v207
	v_lshlrev_b32_e32 v212, 16, v208
	v_and_b32_e32 v213, 0xffff0000, v208
	v_lshlrev_b32_e32 v214, 16, v209
	v_and_b32_e32 v215, 0xffff0000, v209
	v_pk_mul_f32 v[14:15], v[14:15], v[148:149]
	v_pk_mul_f32 v[16:17], v[16:17], v[210:211]
	v_pk_mul_f32 v[10:11], v[10:11], v[212:213]
	v_pk_mul_f32 v[12:13], v[12:13], v[214:215]
	global_store_dwordx4 v141, v[14:17], s[48:49]
	global_store_dwordx4 v141, v[10:13], s[48:49] offset:16
	s_waitcnt vmcnt(24)
	v_lshlrev_b32_e32 v148, 16, v144
	v_and_b32_e32 v149, 0xffff0000, v144
	v_lshlrev_b32_e32 v210, 16, v145
	v_and_b32_e32 v211, 0xffff0000, v145
	v_lshlrev_b32_e32 v212, 16, v146
	v_and_b32_e32 v213, 0xffff0000, v146
	v_lshlrev_b32_e32 v214, 16, v147
	v_and_b32_e32 v215, 0xffff0000, v147
	v_pk_mul_f32 v[6:7], v[6:7], v[148:149]
	v_pk_mul_f32 v[8:9], v[8:9], v[210:211]
	v_pk_mul_f32 v[2:3], v[2:3], v[212:213]
	v_pk_mul_f32 v[4:5], v[4:5], v[214:215]
	global_store_dwordx4 v141, v[6:9], s[48:49] offset:512
	global_store_dwordx4 v141, v[2:5], s[48:49] offset:528
	s_branch .Lbr_done
; __device__ __forceinline__ float bf_lo(unsigned w) { return __uint_as_float(w << 16); }
; __device__ __forceinline__ float bf_hi(unsigned w) { return __uint_as_float(w & 0xffff0000u); }
;     __device__ __forceinline__ void operator()(ACC_T, const Unit& u, int wr, int wc, int fr, int fq) const {
;     ...
;                     const u32x4 gw = *(const u32x4*)(Gt + row * GW + u.z * DM + col0 + bj * HALF);
;                     f32x4 v0 = acc[ai][bj][m][0], v1 = acc[ai][bj][m][1];
;                     v0[0] *= bf_lo(gw.x); v0[1] *= bf_hi(gw.x); v0[2] *= bf_lo(gw.y); v0[3] *= bf_hi(gw.y);
;                     v1[0] *= bf_lo(gw.z); v1[1] *= bf_hi(gw.z); v1[2] *= bf_lo(gw.w); v1[3] *= bf_hi(gw.w);
;                     float* mp = M32 + (size_t)u.pm * (SLOTB / 4) + (row - (size_t)u.pm * BM) * DM + col0 + bj * HALF;
;                     if (u.z > 0) { v0 += *(const f32x4*)mp; v1 += *(const f32x4*)(mp + 4); }
;                     if (u.z < 2) { *(f32x4*)mp = v0; *(f32x4*)(mp + 4) = v1; }
.Lbr_z1:
	global_load_dwordx4 v[144:147], v140, s[24:25]
	global_load_dwordx4 v[154:157], v141, s[46:47]
	global_load_dwordx4 v[158:161], v141, s[46:47] offset:16
	global_load_dwordx4 v[162:165], v140, s[24:25] offset:256
	global_load_dwordx4 v[166:169], v141, s[46:47] offset:512
	global_load_dwordx4 v[170:173], v141, s[46:47] offset:528
	s_add_u32 s24, s24, 0x18000
	s_addc_u32 s25, s25, 0
	s_add_u32 s46, s46, 0x10000
	s_addc_u32 s47, s47, 0
	global_load_dwordx4 v[174:177], v140, s[24:25]
	global_load_dwordx4 v[178:181], v141, s[46:47]
	global_load_dwordx4 v[182:185], v141, s[46:47] offset:16
	global_load_dwordx4 v[186:189], v140, s[24:25] offset:256
	global_load_dwordx4 v[190:193], v141, s[46:47] offset:512
	global_load_dwordx4 v[194:197], v141, s[46:47] offset:528
	s_add_u32 s24, s24, 0x18000
	s_addc_u32 s25, s25, 0
	s_add_u32 s46, s46, 0x10000
	s_addc_u32 s47, s47, 0
	global_load_dwordx4 v[198:201], v140, s[24:25]
	global_load_dwordx4 v[202:205], v141, s[46:47]
	global_load_dwordx4 v[206:209], v141, s[46:47] offset:16
	s_waitcnt vmcnt(12)
	v_lshlrev_b32_e32 v148, 16, v144
	v_and_b32_e32 v149, 0xffff0000, v144
	v_lshlrev_b32_e32 v210, 16, v145
	v_and_b32_e32 v211, 0xffff0000, v145
	v_lshlrev_b32_e32 v212, 16, v146
	v_and_b32_e32 v213, 0xffff0000, v146
	v_lshlrev_b32_e32 v214, 16, v147
	v_and_b32_e32 v215, 0xffff0000, v147
	v_pk_mul_f32 v[126:127], v[126:127], v[148:149]
	v_pk_mul_f32 v[128:129], v[128:129], v[210:211]
	v_pk_mul_f32 v[122:123], v[122:123], v[212:213]
	v_pk_mul_f32 v[124:125], v[124:125], v[214:215]
	v_pk_add_f32 v[126:127], v[126:127], v[154:155]
	v_pk_add_f32 v[128:129], v[128:129], v[156:157]
	v_pk_add_f32 v[122:123], v[122:123], v[158:159]
	v_pk_add_f32 v[124:125], v[124:125], v[160:161]
	global_store_dwordx4 v141, v[126:129], s[48:49]
	global_store_dwordx4 v141, v[122:125], s[48:49] offset:16
	global_load_dwordx4 v[154:157], v140, s[24:25] offset:256
	global_load_dwordx4 v[158:161], v141, s[46:47] offset:512
	global_load_dwordx4 v[144:147], v141, s[46:47] offset:528
	s_add_u32 s24, s24, 0x18000
	s_addc_u32 s25, s25, 0
	s_add_u32 s46, s46, 0x10000
	s_addc_u32 s47, s47, 0
	s_waitcnt vmcnt(14)
	v_lshlrev_b32_e32 v148, 16, v162
	v_and_b32_e32 v149, 0xffff0000, v162
	v_lshlrev_b32_e32 v210, 16, v163
	v_and_b32_e32 v211, 0xffff0000, v163
	v_lshlrev_b32_e32 v212, 16, v164
	v_and_b32_e32 v213, 0xffff0000, v164
	v_lshlrev_b32_e32 v214, 16, v165
	v_and_b32_e32 v215, 0xffff0000, v165
	v_pk_mul_f32 v[118:119], v[118:119], v[148:149]
	v_pk_mul_f32 v[120:121], v[120:121], v[210:211]
	v_pk_mul_f32 v[114:115], v[114:115], v[212:213]
	v_pk_mul_f32 v[116:117], v[116:117], v[214:215]
	v_pk_add_f32 v[118:119], v[118:119], v[166:167]
	v_pk_add_f32 v[120:121], v[120:121], v[168:169]
	v_pk_add_f32 v[114:115], v[114:115], v[170:171]
	v_pk_add_f32 v[116:117], v[116:117], v[172:173]
	global_store_dwordx4 v141, v[118:121], s[48:49] offset:512
	global_store_dwordx4 v141, v[114:117], s[48:49] offset:528
	s_add_u32 s48, s48, 0x10000
	s_addc_u32 s49, s49, 0
	global_load_dwordx4 v[126:129], v140, s[24:25]
	global_load_dwordx4 v[122:125], v141, s[46:47]
	global_load_dwordx4 v[166:169], v141, s[46:47] offset:16
	global_load_dwordx4 v[170:173], v140, s[24:25] offset:256
	global_load_dwordx4 v[162:165], v141, s[46:47] offset:512
	global_load_dwordx4 v[118:121], v141, s[46:47] offset:528
	s_add_u32 s24, s24, 0x78000
	s_addc_u32 s25, s25, 0
	s_add_u32 s46, s46, 0x50000
	s_addc_u32 s47, s47, 0
	s_waitcnt vmcnt(19)
	v_lshlrev_b32_e32 v148, 16, v174
	v_and_b32_e32 v149, 0xffff0000, v174
	v_lshlrev_b32_e32 v210, 16, v175
	v_and_b32_e32 v211, 0xffff0000, v175
	v_lshlrev_b32_e32 v212, 16, v176
	v_and_b32_e32 v213, 0xffff0000, v176
	v_lshlrev_b32_e32 v214, 16, v177
	v_and_b32_e32 v215, 0xffff0000, v177
	v_pk_mul_f32 v[110:111], v[110:111], v[148:149]
	v_pk_mul_f32 v[112:113], v[112:113], v[210:211]
	v_pk_mul_f32 v[106:107], v[106:107], v[212:213]
	v_pk_mul_f32 v[108:109], v[108:109], v[214:215]
	v_pk_add_f32 v[110:111], v[110:111], v[178:179]
	v_pk_add_f32 v[112:113], v[112:113], v[180:181]
	v_pk_add_f32 v[106:107], v[106:107], v[182:183]
	v_pk_add_f32 v[108:109], v[108:109], v[184:185]
	global_store_dwordx4 v141, v[110:113], s[48:49]
	global_store_dwordx4 v141, v[106:109], s[48:49] offset:16
	global_load_dwordx4 v[114:117], v140, s[24:25]
	global_load_dwordx4 v[178:181], v141, s[46:47]
	global_load_dwordx4 v[182:185], v141, s[46:47] offset:16
	global_load_dwordx4 v[174:177], v140, s[24:25] offset:256
	global_load_dwordx4 v[110:113], v141, s[46:47] offset:512
	global_load_dwordx4 v[106:109], v141, s[46:47] offset:528
	s_add_u32 s24, s24, 0x18000
	s_addc_u32 s25, s25, 0
	s_add_u32 s46, s46, 0x10000
	s_addc_u32 s47, s47, 0
	s_waitcnt vmcnt(24)
	v_lshlrev_b32_e32 v148, 16, v186
	v_and_b32_e32 v149, 0xffff0000, v186
	v_lshlrev_b32_e32 v210, 16, v187
	v_and_b32_e32 v211, 0xffff0000, v187
	v_lshlrev_b32_e32 v212, 16, v188
	v_and_b32_e32 v213, 0xffff0000, v188
	v_lshlrev_b32_e32 v214, 16, v189
	v_and_b32_e32 v215, 0xffff0000, v189
	v_pk_mul_f32 v[102:103], v[102:103], v[148:149]
	v_pk_mul_f32 v[104:105], v[104:105], v[210:211]
	v_pk_mul_f32 v[98:99], v[98:99], v[212:213]
	v_pk_mul_f32 v[100:101], v[100:101], v[214:215]
	v_pk_add_f32 v[102:103], v[102:103], v[190:191]
	v_pk_add_f32 v[104:105], v[104:105], v[192:193]
	v_pk_add_f32 v[98:99], v[98:99], v[194:195]
	v_pk_add_f32 v[100:101], v[100:101], v[196:197]
	global_store_dwordx4 v141, v[102:105], s[48:49] offset:512
	global_store_dwordx4 v141, v[98:101], s[48:49] offset:528
	s_add_u32 s48, s48, 0x10000
	s_addc_u32 s49, s49, 0
	global_load_dwordx4 v[190:193], v140, s[24:25]
	global_load_dwordx4 v[194:197], v141, s[46:47]
	global_load_dwordx4 v[186:189], v141, s[46:47] offset:16
	s_waitcnt vmcnt(26)
; __device__ __forceinline__ float bf_lo(unsigned w) { return __uint_as_float(w << 16); }
; __device__ __forceinline__ float bf_hi(unsigned w) { return __uint_as_float(w & 0xffff0000u); }
;     __device__ __forceinline__ void operator()(ACC_T, const Unit& u, int wr, int wc, int fr, int fq) const {
;     ...
;                     const u32x4 gw = *(const u32x4*)(Gt + row * GW + u.z * DM + col0 + bj * HALF);
;                     f32x4 v0 = acc[ai][bj][m][0], v1 = acc[ai][bj][m][1];
;                     v0[0] *= bf_lo(gw.x); v0[1] *= bf_hi(gw.x); v0[2] *= bf_lo(gw.y); v0[3] *= bf_hi(gw.y);
;                     v1[0] *= bf_lo(gw.z); v1[1] *= bf_hi(gw.z); v1[2] *= bf_lo(gw.w); v1[3] *= bf_hi(gw.w);
;                     float* mp = M32 + (size_t)u.pm * (SLOTB / 4) + (row - (size_t)u.pm * BM) * DM + col0 + bj * HALF;
;                     if (u.z > 0) { v0 += *(const f32x4*)mp; v1 += *(const f32x4*)(mp + 4); }
;                     if (u.z < 2) { *(f32x4*)mp = v0; *(f32x4*)(mp + 4) = v1; }
	v_lshlrev_b32_e32 v148, 16, v198
	v_and_b32_e32 v149, 0xffff0000, v198
	v_lshlrev_b32_e32 v210, 16, v199
	v_and_b32_e32 v211, 0xffff0000, v199
	v_lshlrev_b32_e32 v212, 16, v200
	v_and_b32_e32 v213, 0xffff0000, v200
	v_lshlrev_b32_e32 v214, 16, v201
	v_and_b32_e32 v215, 0xffff0000, v201
	v_pk_mul_f32 v[94:95], v[94:95], v[148:149]
	v_pk_mul_f32 v[96:97], v[96:97], v[210:211]
	v_pk_mul_f32 v[90:91], v[90:91], v[212:213]
	v_pk_mul_f32 v[92:93], v[92:93], v[214:215]
	v_pk_add_f32 v[94:95], v[94:95], v[202:203]
	v_pk_add_f32 v[96:97], v[96:97], v[204:205]
	v_pk_add_f32 v[90:91], v[90:91], v[206:207]
	v_pk_add_f32 v[92:93], v[92:93], v[208:209]
	global_store_dwordx4 v141, v[94:97], s[48:49]
	global_store_dwordx4 v141, v[90:93], s[48:49] offset:16
	global_load_dwordx4 v[102:105], v140, s[24:25] offset:256
	global_load_dwordx4 v[98:101], v141, s[46:47] offset:512
	global_load_dwordx4 v[202:205], v141, s[46:47] offset:528
	s_add_u32 s24, s24, 0x18000
	s_addc_u32 s25, s25, 0
	s_add_u32 s46, s46, 0x10000
	s_addc_u32 s47, s47, 0
	global_load_dwordx4 v[206:209], v140, s[24:25]
	global_load_dwordx4 v[198:201], v141, s[46:47]
	global_load_dwordx4 v[94:97], v141, s[46:47] offset:16
	s_waitcnt vmcnt(29)
	v_lshlrev_b32_e32 v148, 16, v154
	v_and_b32_e32 v149, 0xffff0000, v154
	v_lshlrev_b32_e32 v210, 16, v155
	v_and_b32_e32 v211, 0xffff0000, v155
	v_lshlrev_b32_e32 v212, 16, v156
	v_and_b32_e32 v213, 0xffff0000, v156
	v_lshlrev_b32_e32 v214, 16, v157
	v_and_b32_e32 v215, 0xffff0000, v157
	v_pk_mul_f32 v[86:87], v[86:87], v[148:149]
	v_pk_mul_f32 v[88:89], v[88:89], v[210:211]
	v_pk_mul_f32 v[82:83], v[82:83], v[212:213]
	v_pk_mul_f32 v[84:85], v[84:85], v[214:215]
	v_pk_add_f32 v[86:87], v[86:87], v[158:159]
	v_pk_add_f32 v[88:89], v[88:89], v[160:161]
	v_pk_add_f32 v[82:83], v[82:83], v[144:145]
	v_pk_add_f32 v[84:85], v[84:85], v[146:147]
	global_store_dwordx4 v141, v[86:89], s[48:49] offset:512
	global_store_dwordx4 v141, v[82:85], s[48:49] offset:528
	s_add_u32 s48, s48, 0x10000
	s_addc_u32 s49, s49, 0
	global_load_dwordx4 v[90:93], v140, s[24:25] offset:256
	global_load_dwordx4 v[158:161], v141, s[46:47] offset:512
	global_load_dwordx4 v[144:147], v141, s[46:47] offset:528
	s_add_u32 s24, s24, 0x18000
	s_addc_u32 s25, s25, 0
	s_add_u32 s46, s46, 0x10000
	s_addc_u32 s47, s47, 0
	global_load_dwordx4 v[154:157], v140, s[24:25]
	global_load_dwordx4 v[86:89], v141, s[46:47]
	global_load_dwordx4 v[82:85], v141, s[46:47] offset:16
	s_waitcnt vmcnt(32)
	v_lshlrev_b32_e32 v148, 16, v126
	v_and_b32_e32 v149, 0xffff0000, v126
	v_lshlrev_b32_e32 v210, 16, v127
	v_and_b32_e32 v211, 0xffff0000, v127
	v_lshlrev_b32_e32 v212, 16, v128
	v_and_b32_e32 v213, 0xffff0000, v128
	v_lshlrev_b32_e32 v214, 16, v129
	v_and_b32_e32 v215, 0xffff0000, v129
	v_pk_mul_f32 v[78:79], v[78:79], v[148:149]
	v_pk_mul_f32 v[80:81], v[80:81], v[210:211]
	v_pk_mul_f32 v[74:75], v[74:75], v[212:213]
	v_pk_mul_f32 v[76:77], v[76:77], v[214:215]
	v_pk_add_f32 v[78:79], v[78:79], v[122:123]
	v_pk_add_f32 v[80:81], v[80:81], v[124:125]
	v_pk_add_f32 v[74:75], v[74:75], v[166:167]
	v_pk_add_f32 v[76:77], v[76:77], v[168:169]
	global_store_dwordx4 v141, v[78:81], s[48:49]
	global_store_dwordx4 v141, v[74:77], s[48:49] offset:16
	global_load_dwordx4 v[122:125], v140, s[24:25] offset:256
	global_load_dwordx4 v[166:169], v141, s[46:47] offset:512
	global_load_dwordx4 v[126:129], v141, s[46:47] offset:528
	s_waitcnt vmcnt(34)
	v_lshlrev_b32_e32 v148, 16, v170
	v_and_b32_e32 v149, 0xffff0000, v170
	v_lshlrev_b32_e32 v210, 16, v171
	v_and_b32_e32 v211, 0xffff0000, v171
	v_lshlrev_b32_e32 v212, 16, v172
	v_and_b32_e32 v213, 0xffff0000, v172
	v_lshlrev_b32_e32 v214, 16, v173
	v_and_b32_e32 v215, 0xffff0000, v173
	v_pk_mul_f32 v[70:71], v[70:71], v[148:149]
	v_pk_mul_f32 v[72:73], v[72:73], v[210:211]
	v_pk_mul_f32 v[66:67], v[66:67], v[212:213]
	v_pk_mul_f32 v[68:69], v[68:69], v[214:215]
	v_pk_add_f32 v[70:71], v[70:71], v[162:163]
	v_pk_add_f32 v[72:73], v[72:73], v[164:165]
	v_pk_add_f32 v[66:67], v[66:67], v[118:119]
	v_pk_add_f32 v[68:69], v[68:69], v[120:121]
	global_store_dwordx4 v141, v[70:73], s[48:49] offset:512
	global_store_dwordx4 v141, v[66:69], s[48:49] offset:528
	s_add_u32 s48, s48, 0x50000
	s_addc_u32 s49, s49, 0
	s_waitcnt vmcnt(31)
	v_lshlrev_b32_e32 v148, 16, v114
	v_and_b32_e32 v149, 0xffff0000, v114
	v_lshlrev_b32_e32 v210, 16, v115
	v_and_b32_e32 v211, 0xffff0000, v115
	v_lshlrev_b32_e32 v212, 16, v116
	v_and_b32_e32 v213, 0xffff0000, v116
	v_lshlrev_b32_e32 v214, 16, v117
	v_and_b32_e32 v215, 0xffff0000, v117
	v_pk_mul_f32 v[62:63], v[62:63], v[148:149]
	v_pk_mul_f32 v[64:65], v[64:65], v[210:211]
	v_pk_mul_f32 v[58:59], v[58:59], v[212:213]
	v_pk_mul_f32 v[60:61], v[60:61], v[214:215]
	v_pk_add_f32 v[62:63], v[62:63], v[178:179]
	v_pk_add_f32 v[64:65], v[64:65], v[180:181]
	v_pk_add_f32 v[58:59], v[58:59], v[182:183]
	v_pk_add_f32 v[60:61], v[60:61], v[184:185]
	global_store_dwordx4 v141, v[62:65], s[48:49]
	global_store_dwordx4 v141, v[58:61], s[48:49] offset:16
	s_waitcnt vmcnt(30)
; __device__ __forceinline__ float bf_lo(unsigned w) { return __uint_as_float(w << 16); }
; __device__ __forceinline__ float bf_hi(unsigned w) { return __uint_as_float(w & 0xffff0000u); }
; #define PG8_BAR __builtin_amdgcn_s_barrier()
;     __device__ __forceinline__ void operator()(ACC_T, const Unit& u, int wr, int wc, int fr, int fq) const {
;     ...
;                     const u32x4 gw = *(const u32x4*)(Gt + row * GW + u.z * DM + col0 + bj * HALF);
;                     f32x4 v0 = acc[ai][bj][m][0], v1 = acc[ai][bj][m][1];
;                     v0[0] *= bf_lo(gw.x); v0[1] *= bf_hi(gw.x); v0[2] *= bf_lo(gw.y); v0[3] *= bf_hi(gw.y);
;                     v1[0] *= bf_lo(gw.z); v1[1] *= bf_hi(gw.z); v1[2] *= bf_lo(gw.w); v1[3] *= bf_hi(gw.w);
;                     float* mp = M32 + (size_t)u.pm * (SLOTB / 4) + (row - (size_t)u.pm * BM) * DM + col0 + bj * HALF;
;                     if (u.z > 0) { v0 += *(const f32x4*)mp; v1 += *(const f32x4*)(mp + 4); }
;                     if (u.z < 2) { *(f32x4*)mp = v0; *(f32x4*)(mp + 4) = v1; }
; template <class Epi, bool ALIGN_EPI, bool ASLOT = false>
; __device__ __forceinline__ void gemm_phase(LAS unsigned char* lds, const Gemm g, const Sched& S, const Epi& E) {
;     ...
;         cur = nxt; cA = nA; cB = nB; ++ui;
;         if constexpr (ALIGN_EPI) { if (wr == 1) PG8_BAR; }
;     }
	v_lshlrev_b32_e32 v148, 16, v174
	v_and_b32_e32 v149, 0xffff0000, v174
	v_lshlrev_b32_e32 v210, 16, v175
	v_and_b32_e32 v211, 0xffff0000, v175
	v_lshlrev_b32_e32 v212, 16, v176
	v_and_b32_e32 v213, 0xffff0000, v176
	v_lshlrev_b32_e32 v214, 16, v177
	v_and_b32_e32 v215, 0xffff0000, v177
	v_pk_mul_f32 v[54:55], v[54:55], v[148:149]
	v_pk_mul_f32 v[56:57], v[56:57], v[210:211]
	v_pk_mul_f32 v[50:51], v[50:51], v[212:213]
	v_pk_mul_f32 v[52:53], v[52:53], v[214:215]
	v_pk_add_f32 v[54:55], v[54:55], v[110:111]
	v_pk_add_f32 v[56:57], v[56:57], v[112:113]
	v_pk_add_f32 v[50:51], v[50:51], v[106:107]
	v_pk_add_f32 v[52:53], v[52:53], v[108:109]
	global_store_dwordx4 v141, v[54:57], s[48:49] offset:512
	global_store_dwordx4 v141, v[50:53], s[48:49] offset:528
	s_add_u32 s48, s48, 0x10000
	s_addc_u32 s49, s49, 0
	s_waitcnt vmcnt(27)
	v_lshlrev_b32_e32 v148, 16, v190
	v_and_b32_e32 v149, 0xffff0000, v190
	v_lshlrev_b32_e32 v210, 16, v191
	v_and_b32_e32 v211, 0xffff0000, v191
	v_lshlrev_b32_e32 v212, 16, v192
	v_and_b32_e32 v213, 0xffff0000, v192
	v_lshlrev_b32_e32 v214, 16, v193
	v_and_b32_e32 v215, 0xffff0000, v193
	v_pk_mul_f32 v[46:47], v[46:47], v[148:149]
	v_pk_mul_f32 v[48:49], v[48:49], v[210:211]
	v_pk_mul_f32 v[42:43], v[42:43], v[212:213]
	v_pk_mul_f32 v[44:45], v[44:45], v[214:215]
	v_pk_add_f32 v[46:47], v[46:47], v[194:195]
	v_pk_add_f32 v[48:49], v[48:49], v[196:197]
	v_pk_add_f32 v[42:43], v[42:43], v[186:187]
	v_pk_add_f32 v[44:45], v[44:45], v[188:189]
	global_store_dwordx4 v141, v[46:49], s[48:49]
	global_store_dwordx4 v141, v[42:45], s[48:49] offset:16
	s_waitcnt vmcnt(24)
	v_lshlrev_b32_e32 v148, 16, v102
	v_and_b32_e32 v149, 0xffff0000, v102
	v_lshlrev_b32_e32 v210, 16, v103
	v_and_b32_e32 v211, 0xffff0000, v103
	v_lshlrev_b32_e32 v212, 16, v104
	v_and_b32_e32 v213, 0xffff0000, v104
	v_lshlrev_b32_e32 v214, 16, v105
	v_and_b32_e32 v215, 0xffff0000, v105
	v_pk_mul_f32 v[38:39], v[38:39], v[148:149]
	v_pk_mul_f32 v[40:41], v[40:41], v[210:211]
	v_pk_mul_f32 v[34:35], v[34:35], v[212:213]
	v_pk_mul_f32 v[36:37], v[36:37], v[214:215]
	v_pk_add_f32 v[38:39], v[38:39], v[98:99]
	v_pk_add_f32 v[40:41], v[40:41], v[100:101]
	v_pk_add_f32 v[34:35], v[34:35], v[202:203]
	v_pk_add_f32 v[36:37], v[36:37], v[204:205]
	global_store_dwordx4 v141, v[38:41], s[48:49] offset:512
	global_store_dwordx4 v141, v[34:37], s[48:49] offset:528
	s_add_u32 s48, s48, 0x10000
	s_addc_u32 s49, s49, 0
	s_waitcnt vmcnt(23)
	v_lshlrev_b32_e32 v148, 16, v206
	v_and_b32_e32 v149, 0xffff0000, v206
	v_lshlrev_b32_e32 v210, 16, v207
	v_and_b32_e32 v211, 0xffff0000, v207
	v_lshlrev_b32_e32 v212, 16, v208
	v_and_b32_e32 v213, 0xffff0000, v208
	v_lshlrev_b32_e32 v214, 16, v209
	v_and_b32_e32 v215, 0xffff0000, v209
	v_pk_mul_f32 v[30:31], v[30:31], v[148:149]
	v_pk_mul_f32 v[32:33], v[32:33], v[210:211]
	v_pk_mul_f32 v[26:27], v[26:27], v[212:213]
	v_pk_mul_f32 v[28:29], v[28:29], v[214:215]
	v_pk_add_f32 v[30:31], v[30:31], v[198:199]
	v_pk_add_f32 v[32:33], v[32:33], v[200:201]
	v_pk_add_f32 v[26:27], v[26:27], v[94:95]
	v_pk_add_f32 v[28:29], v[28:29], v[96:97]
	global_store_dwordx4 v141, v[30:33], s[48:49]
	global_store_dwordx4 v141, v[26:29], s[48:49] offset:16
	s_waitcnt vmcnt(20)
	v_lshlrev_b32_e32 v148, 16, v90
	v_and_b32_e32 v149, 0xffff0000, v90
	v_lshlrev_b32_e32 v210, 16, v91
	v_and_b32_e32 v211, 0xffff0000, v91
	v_lshlrev_b32_e32 v212, 16, v92
	v_and_b32_e32 v213, 0xffff0000, v92
	v_lshlrev_b32_e32 v214, 16, v93
	v_and_b32_e32 v215, 0xffff0000, v93
	v_pk_mul_f32 v[22:23], v[22:23], v[148:149]
	v_pk_mul_f32 v[24:25], v[24:25], v[210:211]
	v_pk_mul_f32 v[18:19], v[18:19], v[212:213]
	v_pk_mul_f32 v[20:21], v[20:21], v[214:215]
	v_pk_add_f32 v[22:23], v[22:23], v[158:159]
	v_pk_add_f32 v[24:25], v[24:25], v[160:161]
	v_pk_add_f32 v[18:19], v[18:19], v[144:145]
	v_pk_add_f32 v[20:21], v[20:21], v[146:147]
	global_store_dwordx4 v141, v[22:25], s[48:49] offset:512
	global_store_dwordx4 v141, v[18:21], s[48:49] offset:528
	s_add_u32 s48, s48, 0x10000
	s_addc_u32 s49, s49, 0
	s_waitcnt vmcnt(19)
	v_lshlrev_b32_e32 v148, 16, v154
	v_and_b32_e32 v149, 0xffff0000, v154
	v_lshlrev_b32_e32 v210, 16, v155
	v_and_b32_e32 v211, 0xffff0000, v155
	v_lshlrev_b32_e32 v212, 16, v156
	v_and_b32_e32 v213, 0xffff0000, v156
	v_lshlrev_b32_e32 v214, 16, v157
	v_and_b32_e32 v215, 0xffff0000, v157
	v_pk_mul_f32 v[14:15], v[14:15], v[148:149]
	v_pk_mul_f32 v[16:17], v[16:17], v[210:211]
	v_pk_mul_f32 v[10:11], v[10:11], v[212:213]
	v_pk_mul_f32 v[12:13], v[12:13], v[214:215]
	v_pk_add_f32 v[14:15], v[14:15], v[86:87]
	v_pk_add_f32 v[16:17], v[16:17], v[88:89]
	v_pk_add_f32 v[10:11], v[10:11], v[82:83]
	v_pk_add_f32 v[12:13], v[12:13], v[84:85]
	global_store_dwordx4 v141, v[14:17], s[48:49]
	global_store_dwordx4 v141, v[10:13], s[48:49] offset:16
	s_waitcnt vmcnt(16)
	v_lshlrev_b32_e32 v148, 16, v122
	v_and_b32_e32 v149, 0xffff0000, v122
	v_lshlrev_b32_e32 v210, 16, v123
	v_and_b32_e32 v211, 0xffff0000, v123
	v_lshlrev_b32_e32 v212, 16, v124
	v_and_b32_e32 v213, 0xffff0000, v124
	v_lshlrev_b32_e32 v214, 16, v125
	v_and_b32_e32 v215, 0xffff0000, v125
	v_pk_mul_f32 v[6:7], v[6:7], v[148:149]
	v_pk_mul_f32 v[8:9], v[8:9], v[210:211]
	v_pk_mul_f32 v[2:3], v[2:3], v[212:213]
	v_pk_mul_f32 v[4:5], v[4:5], v[214:215]
	v_pk_add_f32 v[6:7], v[6:7], v[166:167]
	v_pk_add_f32 v[8:9], v[8:9], v[168:169]
	v_pk_add_f32 v[2:3], v[2:3], v[126:127]
	v_pk_add_f32 v[4:5], v[4:5], v[128:129]
	global_store_dwordx4 v141, v[6:9], s[48:49] offset:512
	global_store_dwordx4 v141, v[2:5], s[48:49] offset:528
.Lbr_done:
	s_cmp_eq_u32 s58, 2
	s_mov_b64 s[14:15], -1
	s_cbranch_scc1 .LBB0_662
.LBB0_764:
	s_andn2_b64 vcc, exec, s[0:1]
	s_cbranch_vccnz .LBB0_661
	s_barrier
	s_branch .LBB0_661
